# attention loop unrolled x3 (6 tile-steps): ring slot offsets are compile-time constants, so every LDS fragment read is constant-lane-VGPR + immediate; the 10 address VALU adds, the ring-index SALU and
# speedup vs baseline: 1.0054x; 1.0032x over previous
; #define SBAR() __builtin_amdgcn_sched_barrier(0)
; #define KRD(d0) do { if constexpr (VAR & 4) break; const char* a_ = Kc + (((2 * (d0) + hi) ^ sw) << 4); ka[d0] = *reinterpret_cast<const bf16x8*>(a_); kb[d0] = *reinterpret_cast<const bf16x8*>(a_ + 32 * 128); } while (0)
; #define VRD(i) do { if constexpr (VAR & 2) break; lo[(i) & 3] = vtr(vb + v_rd_off((i) >> 2, (i) & 3, 0)); hv[(i) & 3] = vtr(vb + v_rd_off((i) >> 2, (i) & 3, 1)); } while (0)
; #define SUM4(Y, b) do { if constexpr (!(VAR & 8)) { ps += (Y[b] + Y[(b) + 1]) + (Y[(b) + 2] + Y[(b) + 3]); asm volatile("" : "+v"(ps)); } } while (0)
; template <int VAR> ...
;     ...
;     float ps = 0.f;
;     if constexpr (VAR & 4) { ka[0] = qr[0]; ka[1] = qr[1]; ka[2] = qr[2]; ka[3] = qr[3]; kb[0] = qr[0]; kb[1] = qr[1]; kb[2] = qr[2]; kb[3] = qr[3]; }
;     ka[0] = kp[0]; kb[0] = kp[1]; ka[1] = kp[2]; kb[1] = kp[3]; if (dk) glds16(gk, lk); SBAR();
;     { const f32x16 z = f32x16{};
;       QKM(x0, ka[0], qr[0], z);  SUM4(y0, 0); PKA(y0, 0);       SBAR();
;       QKM(x1, kb[0], qr[0], z);  SUM4(y0, 4); PKB(y0, 4, pa0);  KRD(2); if (dv) glds16(gv, lv); SBAR(); }
;     QKM(x0, ka[1], qr[1], x0); SUM4(y0, 8); PKA(y0, 8);       SBAR();
;     QKM(x1, kb[1], qr[1], x1); SUM4(y0, 12); PKB(y0, 12, pa1); KRD(3); if (dv) glds16(gv + 8192, lv + 8192); SBAR();
;     QKM(x0, ka[2], qr[2], x0); SUM4(y1, 0); PKA(y1, 0);       SBAR();
;     QKM(x1, kb[2], qr[2], x1); SUM4(y1, 4); PKB(y1, 4, pa2);  SBAR();
;     QKM(x0, ka[3], qr[3], x0); SUM4(y1, 8); PKA(y1, 8);       SBAR();
;     QKM(x1, kb[3], qr[3], x1); SUM4(y1, 12); PKB(y1, 12, pa3); VRD(0); VRD(1); SBAR();
;     VRD(2); VRD(3); SBAR();
; template <int VAR>
; __device__ __forceinline__ void dattn_block(const BlockRef& cur, const BlockRef& nxt, bool has_next, char* lds, Seam& S, const Outs& OU) {
;     ...
;     bf16x8 kp[4];
;     { const char* a0_ = Kl + s_cur * SHM_K + (((0 + hi) ^ sw) << 4); const char* a1_ = Kl + s_cur * SHM_K + (((2 + hi) ^ sw) << 4);
;       kp[0] = *reinterpret_cast<const bf16x8*>(a0_); kp[1] = *reinterpret_cast<const bf16x8*>(a0_ + 32 * 128); kp[2] = *reinterpret_cast<const bf16x8*>(a1_); kp[3] = *reinterpret_cast<const bf16x8*>(a1_ + 32 * 128); }
;     ...
;     const int TL1 = __builtin_amdgcn_readfirstlane((qlo + 31) / KVBLK + 1);
;     int t = 1;
;     for (; t + 1 < TL1; t += 2) { STEP(pB0, pB1, pA0, pA1, t); STEP(pA0, pA1, pB0, pB1, t + 1); }
.LBB0_354:
	s_waitcnt vmcnt(0) lgkmcnt(0)
	s_barrier
	s_add_i32 s0, s80, 0x10f
	ds_read_b128 v[174:177], v222 offset:57344
	ds_read_b128 v[170:173], v222 offset:61440
	ds_read_b128 v[166:169], v223 offset:57344
	ds_read_b128 v[162:165], v223 offset:61440
	s_lshr_b32 s84, s0, 6
	s_add_i32 s0, s62, 31
	s_ashr_i32 s1, s0, 31
	v_exp_f32_e32 v82, v36
	v_exp_f32_e32 v83, v37
	v_exp_f32_e32 v84, v38
	v_exp_f32_e32 v85, v39
	v_exp_f32_e32 v86, v40
	v_exp_f32_e32 v87, v41
	v_exp_f32_e32 v88, v42
	v_exp_f32_e32 v89, v43
	v_exp_f32_e32 v90, v44
	v_exp_f32_e32 v91, v45
	v_exp_f32_e32 v92, v46
	v_exp_f32_e32 v93, v47
	v_exp_f32_e32 v94, v48
	v_exp_f32_e32 v95, v49
	v_exp_f32_e32 v96, v50
	v_exp_f32_e32 v97, v51
	v_exp_f32_e32 v98, v54
	v_exp_f32_e32 v99, v55
	v_exp_f32_e32 v100, v52
	v_exp_f32_e32 v101, v53
	v_exp_f32_e32 v102, v58
	v_exp_f32_e32 v103, v59
	v_exp_f32_e32 v104, v56
	v_exp_f32_e32 v105, v57
	v_exp_f32_e32 v106, v64
	v_exp_f32_e32 v107, v65
	v_exp_f32_e32 v108, v62
	v_exp_f32_e32 v109, v63
	v_exp_f32_e32 v110, v60
	v_exp_f32_e32 v111, v61
	v_exp_f32_e32 v112, v3
	v_exp_f32_e32 v113, v66
	s_lshr_b32 s1, s1, 26
	s_add_i32 s0, s0, s1
	s_andn2_b64 vcc, exec, s[4:5]
	s_ashr_i32 s60, s0, 6
	s_cmpk_lt_i32 s62, 0x61
	s_cbranch_scc1 .LBB0_402
	s_lshl_b32 s87, s81, 10
	s_cmp_lg_u32 0, -1
	s_cselect_b32 s0, 0, 0
	s_add_i32 s87, s87, s0
	s_lshl_b32 s0, s20, 10
	s_add_i32 s0, s63, s0
	s_lshl_b32 s1, s81, 7
	v_lshl_add_u64 v[4:5], s[18:19], 0, v[198:199]
	v_mov_b32_e32 v227, 0
	s_add_i32 s0, s0, s1
	s_mov_b32 s67, 0
	s_add_i32 s88, s87, 0xc000
	v_cmp_neq_f32_e64 s[4:5], 0, v204
	v_add_u32_e32 v3, s0, v220
	v_lshl_add_u64 v[206:207], v[4:5], 0, s[40:41]
	s_movk_i32 s2, 0x2000
	s_movk_i32 s89, 0x80
	s_mov_b32 s20, 2
	v_mov_b64_e32 v[208:209], v[202:203]
	s_movk_i32 s86, 0x4000
	v_mov_b32_e32 v66, 0
	v_mov_b32_e32 v67, v227
	v_mov_b32_e32 v68, v227
	v_mov_b32_e32 v69, v227
	v_mov_b32_e32 v70, v227
	v_mov_b32_e32 v71, v227
	v_mov_b32_e32 v72, v227
	v_mov_b32_e32 v73, v227
	v_mov_b32_e32 v74, v227
	v_mov_b32_e32 v75, v227
	v_mov_b32_e32 v76, v227
	v_mov_b32_e32 v77, v227
	v_mov_b32_e32 v78, v227
	v_mov_b32_e32 v79, v227
	v_mov_b32_e32 v80, v227
	v_mov_b32_e32 v81, v227
	v_mov_b32_e32 v50, 0
	v_mov_b32_e32 v51, v227
	v_mov_b32_e32 v52, v227
	v_mov_b32_e32 v53, v227
	v_mov_b32_e32 v54, v227
	v_mov_b32_e32 v55, v227
	v_mov_b32_e32 v56, v227
	v_mov_b32_e32 v57, v227
	v_mov_b32_e32 v58, v227
	v_mov_b32_e32 v59, v227
	v_mov_b32_e32 v60, v227
	v_mov_b32_e32 v61, v227
	v_mov_b32_e32 v62, v227
	v_mov_b32_e32 v63, v227
	v_mov_b32_e32 v64, v227
	v_mov_b32_e32 v65, v227
	v_mov_b32_e32 v34, 0
	v_mov_b32_e32 v35, v227
	v_mov_b32_e32 v36, v227
	v_mov_b32_e32 v37, v227
	v_mov_b32_e32 v38, v227
	v_mov_b32_e32 v39, v227
	v_mov_b32_e32 v40, v227
	v_mov_b32_e32 v41, v227
	v_mov_b32_e32 v42, v227
	v_mov_b32_e32 v43, v227
	v_mov_b32_e32 v44, v227
	v_mov_b32_e32 v45, v227
	v_mov_b32_e32 v46, v227
	v_mov_b32_e32 v47, v227
	v_mov_b32_e32 v48, v227
	v_mov_b32_e32 v49, v227
	v_mov_b32_e32 v18, 0
	v_mov_b32_e32 v19, v227
	v_mov_b32_e32 v20, v227
	v_mov_b32_e32 v21, v227
	v_mov_b32_e32 v22, v227
	v_mov_b32_e32 v23, v227
	v_mov_b32_e32 v24, v227
	v_mov_b32_e32 v25, v227
	v_mov_b32_e32 v26, v227
	v_mov_b32_e32 v27, v227
	v_mov_b32_e32 v28, v227
	v_mov_b32_e32 v29, v227
	v_mov_b32_e32 v30, v227
	v_mov_b32_e32 v31, v227
	v_mov_b32_e32 v32, v227
	v_mov_b32_e32 v33, v227
	s_cmp_lg_u64 s[4:5], 0
	s_cselect_b32 s100, 0x80000000, s85
	s_add_i32 s101, s100, 64
	v_add_u32_e32 v237, v215, v216
	v_add_u32_e32 v237, 0x4000, v237
	v_add_u32_e32 v238, v215, v217
	v_add_u32_e32 v238, 0x4000, v238
	v_add_u32_e32 v239, v215, v218
	v_add_u32_e32 v239, 0x4000, v239
	v_add_u32_e32 v240, v215, v219
	v_add_u32_e32 v240, 0x4000, v240
	v_add_u32_e32 v241, 0x2000, v198
	v_add_u32_e32 v242, 0x4000, v198
	v_add_u32_e32 v243, 0x6000, v198
	v_readfirstlane_b32 s92, v198
	v_readfirstlane_b32 s0, v206
	v_readfirstlane_b32 s1, v207
	v_readfirstlane_b32 s90, v208
	v_readfirstlane_b32 s91, v209
	s_sub_u32 s90, s90, s92
	s_subb_u32 s91, s91, 0
	s_add_u32 s92, s92, 0x2000
	s_sub_u32 s0, s0, s92
	s_subb_u32 s1, s1, 0
.LBB0_356:
	s_add_i32 s62, s20, 1
	s_mov_b32 m0, s88
	s_add_i32 s66, s87, 0x8000
	global_load_lds_dwordx4 v198, s[0:1]
	s_waitcnt lgkmcnt(2)
	v_mfma_f32_32x32x16_bf16 v[130:145], v[174:177], v[146:149], 0
	v_add_f32_e32 v4, v82, v83
	v_add_f32_e32 v5, v84, v85
	v_add_f32_e32 v6, v4, v5
	v_cvt_pk_bf16_f32 v4, v82, v83
	v_cvt_pk_bf16_f32 v5, v84, v85
	v_add_f32_e32 v7, v86, v87
	v_add_f32_e32 v8, v88, v89
	v_mfma_f32_32x32x16_bf16 v[114:129], v[170:173], v[146:149], 0
	v_add_f32_e32 v7, v7, v8
	v_add_f32_e32 v8, v7, v6
	v_cvt_pk_bf16_f32 v6, v86, v87
	v_cvt_pk_bf16_f32 v7, v88, v89
	s_mov_b32 m0, s66
	ds_read_b128 v[14:17], v239 offset:40960
	ds_read_b128 v[86:89], v239 offset:45056
	global_load_lds_dwordx4 v198, s[90:91]
	s_waitcnt lgkmcnt(2)
	v_mfma_f32_32x32x16_bf16 v[130:145], v[166:169], v[150:153], v[130:145]
	v_add_f32_e32 v9, v90, v91
	v_add_f32_e32 v10, v92, v93
	v_add_f32_e32 v9, v9, v10
	v_add_f32_e32 v10, v9, v8
	v_cvt_pk_bf16_f32 v8, v90, v91
	v_cvt_pk_bf16_f32 v9, v92, v93
	v_add_f32_e32 v11, v94, v95
	v_add_f32_e32 v13, v96, v97
	v_mfma_f32_32x32x16_bf16 v[114:129], v[162:165], v[150:153], v[114:129]
	v_add_f32_e32 v11, v11, v13
	v_add_f32_e32 v13, v11, v10
	v_cvt_pk_bf16_f32 v10, v94, v95
	v_cvt_pk_bf16_f32 v11, v96, v97
	ds_read_b128 v[90:93], v240 offset:40960
	ds_read_b128 v[82:85], v240 offset:45056
	s_add_i32 m0, s66, 0x2000
	s_cmp_le_i32 s89, s101
	global_load_lds_dwordx4 v241, s[90:91]
	s_waitcnt lgkmcnt(2)
	v_mfma_f32_32x32x16_bf16 v[130:145], v[14:17], v[154:157], v[130:145]
	v_add_f32_e32 v12, v98, v99
	v_add_f32_e32 v94, v100, v101
	v_add_f32_e32 v12, v12, v94
	v_add_f32_e32 v94, v12, v13
	v_cvt_pk_bf16_f32 v12, v98, v99
	v_cvt_pk_bf16_f32 v13, v100, v101
	v_mfma_f32_32x32x16_bf16 v[114:129], v[86:89], v[154:157], v[114:129]
	v_add_f32_e32 v14, v102, v103
	v_add_f32_e32 v15, v104, v105
	v_add_f32_e32 v14, v14, v15
	v_add_f32_e32 v16, v14, v94
	v_cvt_pk_bf16_f32 v14, v102, v103
	v_cvt_pk_bf16_f32 v15, v104, v105
	s_waitcnt lgkmcnt(0)
	v_mfma_f32_32x32x16_bf16 v[130:145], v[90:93], v[158:161], v[130:145]
	v_add_f32_e32 v17, v106, v107
	v_add_f32_e32 v86, v108, v109
	v_add_f32_e32 v17, v17, v86
	v_add_f32_e32 v16, v17, v16
	v_cvt_pk_bf16_f32 v178, v106, v107
	v_cvt_pk_bf16_f32 v179, v108, v109
	v_add_f32_e32 v17, v110, v111
	v_add_f32_e32 v86, v112, v113
	v_add_f32_e32 v17, v17, v86
	v_add_f32_e32 v229, v17, v16
	v_cvt_pk_bf16_f32 v180, v110, v111
	v_cvt_pk_bf16_f32 v181, v112, v113
	v_mfma_f32_32x32x16_bf16 v[114:129], v[82:85], v[158:161], v[114:129]
	ds_read_b64_tr_b16 v[174:175], v214 offset:0
	ds_read_b64_tr_b16 v[176:177], v214 offset:256
	ds_read_b64_tr_b16 v[170:171], v214 offset:4096
	ds_read_b64_tr_b16 v[172:173], v214 offset:4352
	ds_read_b64_tr_b16 v[166:167], v214 offset:8192
	ds_read_b64_tr_b16 v[168:169], v214 offset:8448
	ds_read_b64_tr_b16 v[162:163], v214 offset:12288
	ds_read_b64_tr_b16 v[164:165], v214 offset:12544
	s_cbranch_scc0 .Lp2s_disp1_u0
; #define SBAR() __builtin_amdgcn_sched_barrier(0)
; template <int VAR> ...
;     ...
;     float ps = 0.f;
;     if constexpr (VAR & 4) { ka[0] = qr[0]; ka[1] = qr[1]; ka[2] = qr[2]; ka[3] = qr[3]; kb[0] = qr[0]; kb[1] = qr[1]; kb[2] = qr[2]; kb[3] = qr[3]; }
;     ka[0] = kp[0]; kb[0] = kp[1]; ka[1] = kp[2]; kb[1] = kp[3]; if (dk) glds16(gk, lk); SBAR();
;     { const f32x16 z = f32x16{};
;       QKM(x0, ka[0], qr[0], z);  SUM4(y0, 0); PKA(y0, 0);       SBAR();
;       QKM(x1, kb[0], qr[0], z);  SUM4(y0, 4); PKB(y0, 4, pa0);  KRD(2); if (dv) glds16(gv, lv); SBAR(); }
;     QKM(x0, ka[1], qr[1], x0); SUM4(y0, 8); PKA(y0, 8);       SBAR();
;     QKM(x1, kb[1], qr[1], x1); SUM4(y0, 12); PKB(y0, 12, pa1); KRD(3); if (dv) glds16(gv + 8192, lv + 8192); SBAR();
;     QKM(x0, ka[2], qr[2], x0); SUM4(y1, 0); PKA(y1, 0);       SBAR();
;     QKM(x1, kb[2], qr[2], x1); SUM4(y1, 4); PKB(y1, 4, pa2);  SBAR();
;     QKM(x0, ka[3], qr[3], x0); SUM4(y1, 8); PKA(y1, 8);       SBAR();
;     QKM(x1, kb[3], qr[3], x1); SUM4(y1, 12); PKB(y1, 12, pa3); VRD(0); VRD(1); SBAR();
;     VRD(2); VRD(3); SBAR();
;     if (near) {
;         float tA[4], uA[4], tB[4], uB[4];
;     ...
;         TLD(tA, uA, 0); SBAR(); TLD(tB, uB, 1); SBAR();
;         asm volatile("s_nop 15\n\ts_nop 7" : "+v"(x0), "+v"(x1));
;         TAD(tA, uA, 0); SBAR(); TLD(tA, uA, 2); SBAR(); TAD(tB, uB, 1); SBAR(); TLD(tB, uB, 3); SBAR(); TAD(tA, uA, 2); SBAR(); TAD(tB, uB, 3);
;     ...
;     } else if (__builtin_expect(shift != 0.f, 0)) {
;         asm volatile("s_nop 15\n\ts_nop 7" : "+v"(x0), "+v"(x1));
; #pragma unroll
;         for (int r = 0; r < 16; ++r) { asm volatile("v_sub_f32 %0, %0, %1" : "+v"(x0[r]) : "v"(shift)); asm volatile("v_sub_f32 %0, %0, %1" : "+v"(x1[r]) : "v"(shift)); }
;     }
;     SBAR();
;     ...
;     GAPB(0, pa0); GAPB(1, pa1); GAPB(2, pa2); GAPB(3, pa3); GAPB(4, pa0); GAPB(5, pa1); GAPB(6, pa2); GAPB(7, pa3);
;     GAPB(8, pa0); GAPB(9, pa1); GAPB(10, pa2); GAPB(11, pa3);
;     if (wv == 3) asm volatile("s_waitcnt vmcnt(3)" ::: "memory"); else if (wv == 2) asm volatile("s_waitcnt vmcnt(2)" ::: "memory"); else asm volatile("s_waitcnt vmcnt(0)" ::: "memory");
;     asm volatile("s_waitcnt lgkmcnt(0)\n\ts_barrier" ::: "memory");
;     if (pre) { const char* a0_ = Kn + (((0 + hi) ^ sw) << 4); const char* a1_ = Kn + (((2 + hi) ^ sw) << 4);
.LBB0_367_u0:
	s_waitcnt lgkmcnt(4)
	v_mfma_f32_32x32x16_bf16 v[66:81], v[4:7], v[174:177], v[66:81]
	v_exp_f32_e32 v130, v130
	v_exp_f32_e32 v114, v114
	ds_read_b64_tr_b16 v[98:99], v214 offset:512
	ds_read_b64_tr_b16 v[100:101], v214 offset:768
	v_mfma_f32_32x32x16_bf16 v[66:81], v[8:11], v[170:173], v[66:81]
	v_exp_f32_e32 v131, v131
	v_exp_f32_e32 v115, v115
	ds_read_b64_tr_b16 v[102:103], v214 offset:4608
	ds_read_b64_tr_b16 v[104:105], v214 offset:4864
	s_waitcnt lgkmcnt(4)
	v_mfma_f32_32x32x16_bf16 v[66:81], v[12:15], v[166:169], v[66:81]
	v_exp_f32_e32 v132, v132
	v_exp_f32_e32 v116, v116
	ds_read_b64_tr_b16 v[106:107], v214 offset:8704
	ds_read_b64_tr_b16 v[108:109], v214 offset:8960
	v_mfma_f32_32x32x16_bf16 v[66:81], v[178:181], v[162:165], v[66:81]
	v_exp_f32_e32 v133, v133
	v_exp_f32_e32 v117, v117
	ds_read_b64_tr_b16 v[110:111], v214 offset:12800
	ds_read_b64_tr_b16 v[112:113], v214 offset:13056
	s_waitcnt lgkmcnt(4)
	v_mfma_f32_32x32x16_bf16 v[50:65], v[4:7], v[98:101], v[50:65]
	v_exp_f32_e32 v134, v134
	v_exp_f32_e32 v118, v118
	v_exp_f32_e32 v142, v142
	ds_read_b64_tr_b16 v[82:83], v214 offset:1024
	ds_read_b64_tr_b16 v[84:85], v214 offset:1280
	v_mfma_f32_32x32x16_bf16 v[50:65], v[8:11], v[102:105], v[50:65]
	v_exp_f32_e32 v135, v135
	v_exp_f32_e32 v119, v119
	v_exp_f32_e32 v126, v126
	ds_read_b64_tr_b16 v[86:87], v214 offset:5120
	ds_read_b64_tr_b16 v[88:89], v214 offset:5376
	s_waitcnt lgkmcnt(4)
	v_mfma_f32_32x32x16_bf16 v[50:65], v[12:15], v[106:109], v[50:65]
	v_exp_f32_e32 v136, v136
	v_exp_f32_e32 v120, v120
	v_exp_f32_e32 v143, v143
	ds_read_b64_tr_b16 v[90:91], v214 offset:9216
	ds_read_b64_tr_b16 v[92:93], v214 offset:9472
	v_mfma_f32_32x32x16_bf16 v[50:65], v[178:181], v[110:113], v[50:65]
	v_exp_f32_e32 v137, v137
	v_exp_f32_e32 v121, v121
	v_exp_f32_e32 v127, v127
	ds_read_b64_tr_b16 v[94:95], v214 offset:13312
	ds_read_b64_tr_b16 v[96:97], v214 offset:13568
	s_waitcnt lgkmcnt(4)
	v_mfma_f32_32x32x16_bf16 v[34:49], v[4:7], v[82:85], v[34:49]
	v_exp_f32_e32 v138, v138
	v_exp_f32_e32 v122, v122
	v_exp_f32_e32 v144, v144
	ds_read_b64_tr_b16 v[98:99], v214 offset:1536
	ds_read_b64_tr_b16 v[100:101], v214 offset:1792
	v_mfma_f32_32x32x16_bf16 v[34:49], v[8:11], v[86:89], v[34:49]
	v_exp_f32_e32 v139, v139
	v_exp_f32_e32 v123, v123
	v_exp_f32_e32 v128, v128
	ds_read_b64_tr_b16 v[102:103], v214 offset:5632
	ds_read_b64_tr_b16 v[104:105], v214 offset:5888
	s_waitcnt lgkmcnt(4)
	v_mfma_f32_32x32x16_bf16 v[34:49], v[12:15], v[90:93], v[34:49]
	v_exp_f32_e32 v140, v140
	v_exp_f32_e32 v124, v124
	v_exp_f32_e32 v145, v145
	ds_read_b64_tr_b16 v[106:107], v214 offset:9728
	ds_read_b64_tr_b16 v[108:109], v214 offset:9984
	v_mfma_f32_32x32x16_bf16 v[34:49], v[178:181], v[94:97], v[34:49]
	v_exp_f32_e32 v141, v141
	v_exp_f32_e32 v125, v125
	v_exp_f32_e32 v129, v129
	ds_read_b64_tr_b16 v[110:111], v214 offset:13824
	ds_read_b64_tr_b16 v[112:113], v214 offset:14080
	s_waitcnt vmcnt(3) lgkmcnt(0)
	s_barrier
	ds_read_b128 v[174:177], v237 offset:49152
	ds_read_b128 v[170:173], v237 offset:53248
	ds_read_b128 v[166:169], v238 offset:49152
	ds_read_b128 v[162:165], v238 offset:53248
	v_mfma_f32_32x32x16_bf16 v[18:33], v[4:7], v[98:101], v[18:33]
	v_mfma_f32_32x32x16_bf16 v[18:33], v[8:11], v[102:105], v[18:33]
	v_mfma_f32_32x32x16_bf16 v[18:33], v[12:15], v[106:109], v[18:33]
	v_mfma_f32_32x32x16_bf16 v[18:33], v[178:181], v[110:113], v[18:33]
	s_add_i32 s20, s20, 2
	s_add_i32 m0, s88, 0x2000
	s_mov_b32 s69, s87
	global_load_lds_dwordx4 v241, s[0:1]
	s_waitcnt lgkmcnt(2)
	v_mfma_f32_32x32x16_bf16 v[82:97], v[174:177], v[146:149], 0
	v_add_f32_e32 v4, v130, v131
	v_add_f32_e32 v5, v132, v133
	v_add_f32_e32 v6, v4, v5
	v_cvt_pk_bf16_f32 v4, v130, v131
	v_cvt_pk_bf16_f32 v5, v132, v133
	v_add_f32_e32 v7, v134, v135
	v_add_f32_e32 v8, v136, v137
	v_mfma_f32_32x32x16_bf16 v[98:113], v[170:173], v[146:149], 0
	v_add_f32_e32 v7, v7, v8
	v_add_f32_e32 v8, v7, v6
	v_cvt_pk_bf16_f32 v6, v134, v135
	v_cvt_pk_bf16_f32 v7, v136, v137
	s_mov_b32 m0, s69
	ds_read_b128 v[14:17], v239 offset:49152
	ds_read_b128 v[130:133], v239 offset:53248
	global_load_lds_dwordx4 v242, s[90:91]
	s_waitcnt lgkmcnt(2)
	v_mfma_f32_32x32x16_bf16 v[82:97], v[166:169], v[150:153], v[82:97]
	v_add_f32_e32 v9, v138, v139
	v_add_f32_e32 v10, v140, v141
	v_add_f32_e32 v9, v9, v10
	v_add_f32_e32 v10, v9, v8
	v_cvt_pk_bf16_f32 v8, v138, v139
	v_cvt_pk_bf16_f32 v9, v140, v141
	v_add_f32_e32 v11, v142, v143
	v_add_f32_e32 v134, v144, v145
	v_mfma_f32_32x32x16_bf16 v[98:113], v[162:165], v[150:153], v[98:113]
	v_add_f32_e32 v11, v11, v134
	v_add_f32_e32 v178, v11, v10
	v_cvt_pk_bf16_f32 v10, v142, v143
	v_cvt_pk_bf16_f32 v11, v144, v145
	ds_read_b128 v[138:141], v240 offset:49152
	ds_read_b128 v[134:137], v240 offset:53248
	s_add_i32 m0, s69, 0x2000
	s_cmp_le_i32 s89, s100
	global_load_lds_dwordx4 v243, s[90:91]
	s_waitcnt lgkmcnt(2)
	v_mfma_f32_32x32x16_bf16 v[82:97], v[14:17], v[154:157], v[82:97]
	v_add_f32_e32 v12, v114, v115
	v_add_f32_e32 v13, v116, v117
	v_add_f32_e32 v12, v12, v13
	v_add_f32_e32 v142, v12, v178
	v_cvt_pk_bf16_f32 v12, v114, v115
	v_cvt_pk_bf16_f32 v13, v116, v117
	v_mfma_f32_32x32x16_bf16 v[98:113], v[130:133], v[154:157], v[98:113]
	v_add_f32_e32 v14, v118, v119
	v_add_f32_e32 v15, v120, v121
	v_add_f32_e32 v14, v14, v15
	v_add_f32_e32 v16, v14, v142
	v_cvt_pk_bf16_f32 v14, v118, v119
	v_cvt_pk_bf16_f32 v15, v120, v121
	s_waitcnt lgkmcnt(0)
	v_mfma_f32_32x32x16_bf16 v[82:97], v[138:141], v[158:161], v[82:97]
	v_add_f32_e32 v17, v122, v123
	v_add_f32_e32 v130, v124, v125
	v_add_f32_e32 v17, v17, v130
	v_add_f32_e32 v16, v17, v16
	v_cvt_pk_bf16_f32 v178, v122, v123
	v_cvt_pk_bf16_f32 v179, v124, v125
	v_add_f32_e32 v17, v126, v127
	v_add_f32_e32 v130, v128, v129
	v_add_f32_e32 v17, v17, v130
	v_add_f32_e32 v16, v17, v16
	v_cvt_pk_bf16_f32 v180, v126, v127
	v_cvt_pk_bf16_f32 v181, v128, v129
	v_mfma_f32_32x32x16_bf16 v[98:113], v[134:137], v[158:161], v[98:113]
	ds_read_b64_tr_b16 v[194:195], v214 offset:16384
	ds_read_b64_tr_b16 v[196:197], v214 offset:16640
	ds_read_b64_tr_b16 v[190:191], v214 offset:20480
	ds_read_b64_tr_b16 v[192:193], v214 offset:20736
	ds_read_b64_tr_b16 v[186:187], v214 offset:24576
	ds_read_b64_tr_b16 v[188:189], v214 offset:24832
	ds_read_b64_tr_b16 v[182:183], v214 offset:28672
	ds_read_b64_tr_b16 v[184:185], v214 offset:28928
	s_cbranch_scc0 .Lp2s_disp2_u0
; #define SBAR() __builtin_amdgcn_sched_barrier(0)
; template <int VAR> ...
;     ...
;     GAPB(0, pa0); GAPB(1, pa1); GAPB(2, pa2); GAPB(3, pa3); GAPB(4, pa0); GAPB(5, pa1); GAPB(6, pa2); GAPB(7, pa3);
;     GAPB(8, pa0); GAPB(9, pa1); GAPB(10, pa2); GAPB(11, pa3);
;     if (wv == 3) asm volatile("s_waitcnt vmcnt(3)" ::: "memory"); else if (wv == 2) asm volatile("s_waitcnt vmcnt(2)" ::: "memory"); else asm volatile("s_waitcnt vmcnt(0)" ::: "memory");
;     asm volatile("s_waitcnt lgkmcnt(0)\n\ts_barrier" ::: "memory");
;     if (pre) { const char* a0_ = Kn + (((0 + hi) ^ sw) << 4); const char* a1_ = Kn + (((2 + hi) ^ sw) << 4);
;         kp[0] = *reinterpret_cast<const bf16x8*>(a0_); kp[1] = *reinterpret_cast<const bf16x8*>(a0_ + 32 * 128); kp[2] = *reinterpret_cast<const bf16x8*>(a1_); kp[3] = *reinterpret_cast<const bf16x8*>(a1_ + 32 * 128); }
;     SBAR();
;     GAPB(12, pa0); GAPB(13, pa1); GAPB(14, pa2); GAPB(15, pa3);
; template <int VAR>
; __device__ __forceinline__ void dattn_block(const BlockRef& cur, const BlockRef& nxt, bool has_next, char* lds, Seam& S, const Outs& OU) {
;     ...
;     const int TL1 = __builtin_amdgcn_readfirstlane((qlo + 31) / KVBLK + 1);
;     int t = 1;
;     for (; t + 1 < TL1; t += 2) { STEP(pB0, pB1, pA0, pA1, t); STEP(pA0, pA1, pB0, pB1, t + 1); }
.LBB0_385_u0:
	s_waitcnt lgkmcnt(4)
	v_mfma_f32_32x32x16_bf16 v[66:81], v[4:7], v[194:197], v[66:81]
	v_exp_f32_e32 v82, v82
	v_exp_f32_e32 v98, v98
	ds_read_b64_tr_b16 v[114:115], v214 offset:16896
	ds_read_b64_tr_b16 v[116:117], v214 offset:17152
	v_mfma_f32_32x32x16_bf16 v[66:81], v[8:11], v[190:193], v[66:81]
	v_exp_f32_e32 v83, v83
	v_exp_f32_e32 v99, v99
	ds_read_b64_tr_b16 v[118:119], v214 offset:20992
	ds_read_b64_tr_b16 v[120:121], v214 offset:21248
	s_waitcnt lgkmcnt(4)
	v_mfma_f32_32x32x16_bf16 v[66:81], v[12:15], v[186:189], v[66:81]
	v_exp_f32_e32 v84, v84
	v_exp_f32_e32 v100, v100
	ds_read_b64_tr_b16 v[122:123], v214 offset:25088
	ds_read_b64_tr_b16 v[124:125], v214 offset:25344
	v_mfma_f32_32x32x16_bf16 v[66:81], v[178:181], v[182:185], v[66:81]
	v_exp_f32_e32 v85, v85
	v_exp_f32_e32 v101, v101
	ds_read_b64_tr_b16 v[126:127], v214 offset:29184
	ds_read_b64_tr_b16 v[128:129], v214 offset:29440
	s_waitcnt lgkmcnt(4)
	v_mfma_f32_32x32x16_bf16 v[50:65], v[4:7], v[114:117], v[50:65]
	v_exp_f32_e32 v86, v86
	v_exp_f32_e32 v102, v102
	v_exp_f32_e32 v94, v94
	ds_read_b64_tr_b16 v[130:131], v214 offset:17408
	ds_read_b64_tr_b16 v[132:133], v214 offset:17664
	v_mfma_f32_32x32x16_bf16 v[50:65], v[8:11], v[118:121], v[50:65]
	v_exp_f32_e32 v87, v87
	v_exp_f32_e32 v103, v103
	v_exp_f32_e32 v110, v110
	ds_read_b64_tr_b16 v[134:135], v214 offset:21504
	ds_read_b64_tr_b16 v[136:137], v214 offset:21760
	s_waitcnt lgkmcnt(4)
	v_mfma_f32_32x32x16_bf16 v[50:65], v[12:15], v[122:125], v[50:65]
	v_exp_f32_e32 v88, v88
	v_exp_f32_e32 v104, v104
	v_exp_f32_e32 v95, v95
	ds_read_b64_tr_b16 v[138:139], v214 offset:25600
	ds_read_b64_tr_b16 v[140:141], v214 offset:25856
	v_mfma_f32_32x32x16_bf16 v[50:65], v[178:181], v[126:129], v[50:65]
	v_exp_f32_e32 v89, v89
	v_exp_f32_e32 v105, v105
	v_exp_f32_e32 v111, v111
	ds_read_b64_tr_b16 v[142:143], v214 offset:29696
	ds_read_b64_tr_b16 v[144:145], v214 offset:29952
	s_waitcnt lgkmcnt(4)
	v_mfma_f32_32x32x16_bf16 v[34:49], v[4:7], v[130:133], v[34:49]
	v_exp_f32_e32 v90, v90
	v_exp_f32_e32 v106, v106
	v_exp_f32_e32 v96, v96
	ds_read_b64_tr_b16 v[114:115], v214 offset:17920
	ds_read_b64_tr_b16 v[116:117], v214 offset:18176
	v_mfma_f32_32x32x16_bf16 v[34:49], v[8:11], v[134:137], v[34:49]
	v_exp_f32_e32 v91, v91
	v_exp_f32_e32 v107, v107
	v_exp_f32_e32 v112, v112
	ds_read_b64_tr_b16 v[118:119], v214 offset:22016
	ds_read_b64_tr_b16 v[120:121], v214 offset:22272
	s_waitcnt lgkmcnt(4)
	v_mfma_f32_32x32x16_bf16 v[34:49], v[12:15], v[138:141], v[34:49]
	v_exp_f32_e32 v92, v92
	v_exp_f32_e32 v108, v108
	v_exp_f32_e32 v97, v97
	ds_read_b64_tr_b16 v[122:123], v214 offset:26112
	ds_read_b64_tr_b16 v[124:125], v214 offset:26368
	v_mfma_f32_32x32x16_bf16 v[34:49], v[178:181], v[142:145], v[34:49]
	v_exp_f32_e32 v93, v93
	v_exp_f32_e32 v109, v109
	v_exp_f32_e32 v113, v113
	ds_read_b64_tr_b16 v[126:127], v214 offset:30208
	ds_read_b64_tr_b16 v[128:129], v214 offset:30464
	s_waitcnt vmcnt(3) lgkmcnt(0)
	s_barrier
	s_cmp_gt_i32 s62, s60
	s_cbranch_scc1 .LBB0_394_u0
	ds_read_b128 v[174:177], v237 offset:32768
	ds_read_b128 v[170:173], v237 offset:36864
	ds_read_b128 v[166:169], v238 offset:32768
	ds_read_b128 v[162:165], v238 offset:36864
.LBB0_394_u0:
	v_add_f32_e32 v17, v227, v229
	v_mfma_f32_32x32x16_bf16 v[18:33], v[4:7], v[114:117], v[18:33]
	v_mfma_f32_32x32x16_bf16 v[18:33], v[8:11], v[118:121], v[18:33]
	v_mfma_f32_32x32x16_bf16 v[18:33], v[12:15], v[122:125], v[18:33]
	v_mfma_f32_32x32x16_bf16 v[18:33], v[178:181], v[126:129], v[18:33]
	s_addk_i32 s89, 0x80
	v_add_f32_e32 v227, v17, v16
	v_add_u32_e32 v3, 0xfffffe00, v3
	s_add_u32 s90, s90, 0x8000
	s_addc_u32 s91, s91, 0
	s_add_u32 s0, s0, 0x4000
	s_addc_u32 s1, s1, 0
	s_cmp_lt_i32 s62, s60
	s_cbranch_scc0 .Lp2u_exit0

; #define SBAR() __builtin_amdgcn_sched_barrier(0)
; #define VRD(i) do { if constexpr (VAR & 2) break; lo[(i) & 3] = vtr(vb + v_rd_off((i) >> 2, (i) & 3, 0)); hv[(i) & 3] = vtr(vb + v_rd_off((i) >> 2, (i) & 3, 1)); } while (0)
; template <int VAR> ...
;     ...
;     float ps = 0.f;
;     if constexpr (VAR & 4) { ka[0] = qr[0]; ka[1] = qr[1]; ka[2] = qr[2]; ka[3] = qr[3]; kb[0] = qr[0]; kb[1] = qr[1]; kb[2] = qr[2]; kb[3] = qr[3]; }
;     ka[0] = kp[0]; kb[0] = kp[1]; ka[1] = kp[2]; kb[1] = kp[3]; if (dk) glds16(gk, lk); SBAR();
;     { const f32x16 z = f32x16{};
;       QKM(x0, ka[0], qr[0], z);  SUM4(y0, 0); PKA(y0, 0);       SBAR();
;       QKM(x1, kb[0], qr[0], z);  SUM4(y0, 4); PKB(y0, 4, pa0);  KRD(2); if (dv) glds16(gv, lv); SBAR(); }
;     QKM(x0, ka[1], qr[1], x0); SUM4(y0, 8); PKA(y0, 8);       SBAR();
;     QKM(x1, kb[1], qr[1], x1); SUM4(y0, 12); PKB(y0, 12, pa1); KRD(3); if (dv) glds16(gv + 8192, lv + 8192); SBAR();
;     QKM(x0, ka[2], qr[2], x0); SUM4(y1, 0); PKA(y1, 0);       SBAR();
;     QKM(x1, kb[2], qr[2], x1); SUM4(y1, 4); PKB(y1, 4, pa2);  SBAR();
;     QKM(x0, ka[3], qr[3], x0); SUM4(y1, 8); PKA(y1, 8);       SBAR();
;     QKM(x1, kb[3], qr[3], x1); SUM4(y1, 12); PKB(y1, 12, pa3); VRD(0); VRD(1); SBAR();
;     VRD(2); VRD(3); SBAR();
;     if (near) {
;         float tA[4], uA[4], tB[4], uB[4];
;     ...
;         TLD(tA, uA, 0); SBAR(); TLD(tB, uB, 1); SBAR();
;         asm volatile("s_nop 15\n\ts_nop 7" : "+v"(x0), "+v"(x1));
;         TAD(tA, uA, 0); SBAR(); TLD(tA, uA, 2); SBAR(); TAD(tB, uB, 1); SBAR(); TLD(tB, uB, 3); SBAR(); TAD(tA, uA, 2); SBAR(); TAD(tB, uB, 3);
;     ...
;     } else if (__builtin_expect(shift != 0.f, 0)) {
;         asm volatile("s_nop 15\n\ts_nop 7" : "+v"(x0), "+v"(x1));
; #pragma unroll
;         for (int r = 0; r < 16; ++r) { asm volatile("v_sub_f32 %0, %0, %1" : "+v"(x0[r]) : "v"(shift)); asm volatile("v_sub_f32 %0, %0, %1" : "+v"(x1[r]) : "v"(shift)); }
;     }
;     SBAR();
;     ...
;     GAPB(0, pa0); GAPB(1, pa1); GAPB(2, pa2); GAPB(3, pa3); GAPB(4, pa0); GAPB(5, pa1); GAPB(6, pa2); GAPB(7, pa3);
;     GAPB(8, pa0); GAPB(9, pa1); GAPB(10, pa2); GAPB(11, pa3);
;     if (wv == 3) asm volatile("s_waitcnt vmcnt(3)" ::: "memory"); else if (wv == 2) asm volatile("s_waitcnt vmcnt(2)" ::: "memory"); else asm volatile("s_waitcnt vmcnt(0)" ::: "memory");
;     asm volatile("s_waitcnt lgkmcnt(0)\n\ts_barrier" ::: "memory");
.Lp2u_top1:
	s_add_i32 s62, s20, 1
	s_add_i32 m0, s88, 0x4000
	s_add_i32 s66, s87, 0x4000
	global_load_lds_dwordx4 v198, s[0:1]
	s_waitcnt lgkmcnt(2)
	v_mfma_f32_32x32x16_bf16 v[130:145], v[174:177], v[146:149], 0
	v_add_f32_e32 v4, v82, v83
	v_add_f32_e32 v5, v84, v85
	v_add_f32_e32 v6, v4, v5
	v_cvt_pk_bf16_f32 v4, v82, v83
	v_cvt_pk_bf16_f32 v5, v84, v85
	v_add_f32_e32 v7, v86, v87
	v_add_f32_e32 v8, v88, v89
	v_mfma_f32_32x32x16_bf16 v[114:129], v[170:173], v[146:149], 0
	v_add_f32_e32 v7, v7, v8
	v_add_f32_e32 v8, v7, v6
	v_cvt_pk_bf16_f32 v6, v86, v87
	v_cvt_pk_bf16_f32 v7, v88, v89
	s_mov_b32 m0, s66
	ds_read_b128 v[14:17], v239 offset:32768
	ds_read_b128 v[86:89], v239 offset:36864
	global_load_lds_dwordx4 v198, s[90:91]
	s_waitcnt lgkmcnt(2)
	v_mfma_f32_32x32x16_bf16 v[130:145], v[166:169], v[150:153], v[130:145]
	v_add_f32_e32 v9, v90, v91
	v_add_f32_e32 v10, v92, v93
	v_add_f32_e32 v9, v9, v10
	v_add_f32_e32 v10, v9, v8
	v_cvt_pk_bf16_f32 v8, v90, v91
	v_cvt_pk_bf16_f32 v9, v92, v93
	v_add_f32_e32 v11, v94, v95
	v_add_f32_e32 v13, v96, v97
	v_mfma_f32_32x32x16_bf16 v[114:129], v[162:165], v[150:153], v[114:129]
	v_add_f32_e32 v11, v11, v13
	v_add_f32_e32 v13, v11, v10
	v_cvt_pk_bf16_f32 v10, v94, v95
	v_cvt_pk_bf16_f32 v11, v96, v97
	ds_read_b128 v[90:93], v240 offset:32768
	ds_read_b128 v[82:85], v240 offset:36864
	s_add_i32 m0, s66, 0x2000
	s_cmp_le_i32 s89, s101
	global_load_lds_dwordx4 v241, s[90:91]
	s_waitcnt lgkmcnt(2)
	v_mfma_f32_32x32x16_bf16 v[130:145], v[14:17], v[154:157], v[130:145]
	v_add_f32_e32 v12, v98, v99
	v_add_f32_e32 v94, v100, v101
	v_add_f32_e32 v12, v12, v94
	v_add_f32_e32 v94, v12, v13
	v_cvt_pk_bf16_f32 v12, v98, v99
	v_cvt_pk_bf16_f32 v13, v100, v101
	v_mfma_f32_32x32x16_bf16 v[114:129], v[86:89], v[154:157], v[114:129]
	v_add_f32_e32 v14, v102, v103
	v_add_f32_e32 v15, v104, v105
	v_add_f32_e32 v14, v14, v15
	v_add_f32_e32 v16, v14, v94
	v_cvt_pk_bf16_f32 v14, v102, v103
	v_cvt_pk_bf16_f32 v15, v104, v105
	s_waitcnt lgkmcnt(0)
	v_mfma_f32_32x32x16_bf16 v[130:145], v[90:93], v[158:161], v[130:145]
	v_add_f32_e32 v17, v106, v107
	v_add_f32_e32 v86, v108, v109
	v_add_f32_e32 v17, v17, v86
	v_add_f32_e32 v16, v17, v16
	v_cvt_pk_bf16_f32 v178, v106, v107
	v_cvt_pk_bf16_f32 v179, v108, v109
	v_add_f32_e32 v17, v110, v111
	v_add_f32_e32 v86, v112, v113
	v_add_f32_e32 v17, v17, v86
	v_add_f32_e32 v229, v17, v16
	v_cvt_pk_bf16_f32 v180, v110, v111
	v_cvt_pk_bf16_f32 v181, v112, v113
	v_mfma_f32_32x32x16_bf16 v[114:129], v[82:85], v[158:161], v[114:129]
	ds_read_b64_tr_b16 v[174:175], v214 offset:32768
	ds_read_b64_tr_b16 v[176:177], v214 offset:33024
	ds_read_b64_tr_b16 v[170:171], v214 offset:36864
	ds_read_b64_tr_b16 v[172:173], v214 offset:37120
	ds_read_b64_tr_b16 v[166:167], v214 offset:40960
	ds_read_b64_tr_b16 v[168:169], v214 offset:41216
	ds_read_b64_tr_b16 v[162:163], v214 offset:45056
	ds_read_b64_tr_b16 v[164:165], v214 offset:45312
	s_cbranch_scc0 .Lp2s_disp1_u1
.LBB0_367_u1:
	s_waitcnt lgkmcnt(4)
	v_mfma_f32_32x32x16_bf16 v[66:81], v[4:7], v[174:177], v[66:81]
	v_exp_f32_e32 v130, v130
	v_exp_f32_e32 v114, v114
	ds_read_b64_tr_b16 v[98:99], v214 offset:33280
	ds_read_b64_tr_b16 v[100:101], v214 offset:33536
	v_mfma_f32_32x32x16_bf16 v[66:81], v[8:11], v[170:173], v[66:81]
	v_exp_f32_e32 v131, v131
	v_exp_f32_e32 v115, v115
	ds_read_b64_tr_b16 v[102:103], v214 offset:37376
	ds_read_b64_tr_b16 v[104:105], v214 offset:37632
	s_waitcnt lgkmcnt(4)
	v_mfma_f32_32x32x16_bf16 v[66:81], v[12:15], v[166:169], v[66:81]
	v_exp_f32_e32 v132, v132
	v_exp_f32_e32 v116, v116
	ds_read_b64_tr_b16 v[106:107], v214 offset:41472
	ds_read_b64_tr_b16 v[108:109], v214 offset:41728
	v_mfma_f32_32x32x16_bf16 v[66:81], v[178:181], v[162:165], v[66:81]
	v_exp_f32_e32 v133, v133
	v_exp_f32_e32 v117, v117
	ds_read_b64_tr_b16 v[110:111], v214 offset:45568
	ds_read_b64_tr_b16 v[112:113], v214 offset:45824
	s_waitcnt lgkmcnt(4)
	v_mfma_f32_32x32x16_bf16 v[50:65], v[4:7], v[98:101], v[50:65]
	v_exp_f32_e32 v134, v134
	v_exp_f32_e32 v118, v118
	v_exp_f32_e32 v142, v142
	ds_read_b64_tr_b16 v[82:83], v214 offset:33792
	ds_read_b64_tr_b16 v[84:85], v214 offset:34048
	v_mfma_f32_32x32x16_bf16 v[50:65], v[8:11], v[102:105], v[50:65]
	v_exp_f32_e32 v135, v135
	v_exp_f32_e32 v119, v119
	v_exp_f32_e32 v126, v126
	ds_read_b64_tr_b16 v[86:87], v214 offset:37888
	ds_read_b64_tr_b16 v[88:89], v214 offset:38144
	s_waitcnt lgkmcnt(4)
	v_mfma_f32_32x32x16_bf16 v[50:65], v[12:15], v[106:109], v[50:65]
	v_exp_f32_e32 v136, v136
	v_exp_f32_e32 v120, v120
	v_exp_f32_e32 v143, v143
	ds_read_b64_tr_b16 v[90:91], v214 offset:41984
	ds_read_b64_tr_b16 v[92:93], v214 offset:42240
	v_mfma_f32_32x32x16_bf16 v[50:65], v[178:181], v[110:113], v[50:65]
	v_exp_f32_e32 v137, v137
	v_exp_f32_e32 v121, v121
	v_exp_f32_e32 v127, v127
	ds_read_b64_tr_b16 v[94:95], v214 offset:46080
	ds_read_b64_tr_b16 v[96:97], v214 offset:46336
	s_waitcnt lgkmcnt(4)
	v_mfma_f32_32x32x16_bf16 v[34:49], v[4:7], v[82:85], v[34:49]
	v_exp_f32_e32 v138, v138
	v_exp_f32_e32 v122, v122
	v_exp_f32_e32 v144, v144
	ds_read_b64_tr_b16 v[98:99], v214 offset:34304
	ds_read_b64_tr_b16 v[100:101], v214 offset:34560
	v_mfma_f32_32x32x16_bf16 v[34:49], v[8:11], v[86:89], v[34:49]
	v_exp_f32_e32 v139, v139
	v_exp_f32_e32 v123, v123
	v_exp_f32_e32 v128, v128
	ds_read_b64_tr_b16 v[102:103], v214 offset:38400
	ds_read_b64_tr_b16 v[104:105], v214 offset:38656
	s_waitcnt lgkmcnt(4)
	v_mfma_f32_32x32x16_bf16 v[34:49], v[12:15], v[90:93], v[34:49]
	v_exp_f32_e32 v140, v140
	v_exp_f32_e32 v124, v124
	v_exp_f32_e32 v145, v145
	ds_read_b64_tr_b16 v[106:107], v214 offset:42496
	ds_read_b64_tr_b16 v[108:109], v214 offset:42752
	v_mfma_f32_32x32x16_bf16 v[34:49], v[178:181], v[94:97], v[34:49]
	v_exp_f32_e32 v141, v141
	v_exp_f32_e32 v125, v125
	v_exp_f32_e32 v129, v129
	ds_read_b64_tr_b16 v[110:111], v214 offset:46592
	ds_read_b64_tr_b16 v[112:113], v214 offset:46848
	s_waitcnt vmcnt(3) lgkmcnt(0)
	s_barrier
; #define SBAR() __builtin_amdgcn_sched_barrier(0)
; #define KRD(d0) do { if constexpr (VAR & 4) break; const char* a_ = Kc + (((2 * (d0) + hi) ^ sw) << 4); ka[d0] = *reinterpret_cast<const bf16x8*>(a_); kb[d0] = *reinterpret_cast<const bf16x8*>(a_ + 32 * 128); } while (0)
; #define VRD(i) do { if constexpr (VAR & 2) break; lo[(i) & 3] = vtr(vb + v_rd_off((i) >> 2, (i) & 3, 0)); hv[(i) & 3] = vtr(vb + v_rd_off((i) >> 2, (i) & 3, 1)); } while (0)
; #define SUM4(Y, b) do { if constexpr (!(VAR & 8)) { ps += (Y[b] + Y[(b) + 1]) + (Y[(b) + 2] + Y[(b) + 3]); asm volatile("" : "+v"(ps)); } } while (0)
; #define PKA(Y, b) do { if constexpr (!(VAR & 8)) { a0 = cvtpk(Y[b], Y[(b) + 1]); a1 = cvtpk(Y[(b) + 2], Y[(b) + 3]); } } while (0)
; #define QKM(X, KF, QF, C) do { if constexpr (VAR & 4) { X = C; asm volatile("" : "+v"(X)); } else X = __builtin_amdgcn_mfma_f32_32x32x16_bf16(KF, QF, C, 0, 0, 0); } while (0)
; template <int VAR> ...
;     ...
;     float ps = 0.f;
;     if constexpr (VAR & 4) { ka[0] = qr[0]; ka[1] = qr[1]; ka[2] = qr[2]; ka[3] = qr[3]; kb[0] = qr[0]; kb[1] = qr[1]; kb[2] = qr[2]; kb[3] = qr[3]; }
;     ka[0] = kp[0]; kb[0] = kp[1]; ka[1] = kp[2]; kb[1] = kp[3]; if (dk) glds16(gk, lk); SBAR();
;     { const f32x16 z = f32x16{};
;       QKM(x0, ka[0], qr[0], z);  SUM4(y0, 0); PKA(y0, 0);       SBAR();
;       QKM(x1, kb[0], qr[0], z);  SUM4(y0, 4); PKB(y0, 4, pa0);  KRD(2); if (dv) glds16(gv, lv); SBAR(); }
;     QKM(x0, ka[1], qr[1], x0); SUM4(y0, 8); PKA(y0, 8);       SBAR();
;     QKM(x1, kb[1], qr[1], x1); SUM4(y0, 12); PKB(y0, 12, pa1); KRD(3); if (dv) glds16(gv + 8192, lv + 8192); SBAR();
;     QKM(x0, ka[2], qr[2], x0); SUM4(y1, 0); PKA(y1, 0);       SBAR();
;     QKM(x1, kb[2], qr[2], x1); SUM4(y1, 4); PKB(y1, 4, pa2);  SBAR();
;     QKM(x0, ka[3], qr[3], x0); SUM4(y1, 8); PKA(y1, 8);       SBAR();
;     QKM(x1, kb[3], qr[3], x1); SUM4(y1, 12); PKB(y1, 12, pa3); VRD(0); VRD(1); SBAR();
;     VRD(2); VRD(3); SBAR();
;     ...
;     if (pre) { const char* a0_ = Kn + (((0 + hi) ^ sw) << 4); const char* a1_ = Kn + (((2 + hi) ^ sw) << 4);
;         kp[0] = *reinterpret_cast<const bf16x8*>(a0_); kp[1] = *reinterpret_cast<const bf16x8*>(a0_ + 32 * 128); kp[2] = *reinterpret_cast<const bf16x8*>(a1_); kp[3] = *reinterpret_cast<const bf16x8*>(a1_ + 32 * 128); }
;     SBAR();
;     GAPB(12, pa0); GAPB(13, pa1); GAPB(14, pa2); GAPB(15, pa3);
;     l_reg += ps;
	ds_read_b128 v[174:177], v237 offset:40960
	ds_read_b128 v[170:173], v237 offset:45056
	ds_read_b128 v[166:169], v238 offset:40960
	ds_read_b128 v[162:165], v238 offset:45056
	v_mfma_f32_32x32x16_bf16 v[18:33], v[4:7], v[98:101], v[18:33]
	v_mfma_f32_32x32x16_bf16 v[18:33], v[8:11], v[102:105], v[18:33]
	v_mfma_f32_32x32x16_bf16 v[18:33], v[12:15], v[106:109], v[18:33]
	v_mfma_f32_32x32x16_bf16 v[18:33], v[178:181], v[110:113], v[18:33]
	s_add_i32 s20, s20, 2
	s_mov_b32 m0, s88
	s_add_i32 s69, s87, 0x8000
	global_load_lds_dwordx4 v241, s[0:1]
	s_waitcnt lgkmcnt(2)
	v_mfma_f32_32x32x16_bf16 v[82:97], v[174:177], v[146:149], 0
	v_add_f32_e32 v4, v130, v131
	v_add_f32_e32 v5, v132, v133
	v_add_f32_e32 v6, v4, v5
	v_cvt_pk_bf16_f32 v4, v130, v131
	v_cvt_pk_bf16_f32 v5, v132, v133
	v_add_f32_e32 v7, v134, v135
	v_add_f32_e32 v8, v136, v137
	v_mfma_f32_32x32x16_bf16 v[98:113], v[170:173], v[146:149], 0
	v_add_f32_e32 v7, v7, v8
	v_add_f32_e32 v8, v7, v6
	v_cvt_pk_bf16_f32 v6, v134, v135
	v_cvt_pk_bf16_f32 v7, v136, v137
	s_mov_b32 m0, s69
	ds_read_b128 v[14:17], v239 offset:40960
	ds_read_b128 v[130:133], v239 offset:45056
	global_load_lds_dwordx4 v242, s[90:91]
	s_waitcnt lgkmcnt(2)
	v_mfma_f32_32x32x16_bf16 v[82:97], v[166:169], v[150:153], v[82:97]
	v_add_f32_e32 v9, v138, v139
	v_add_f32_e32 v10, v140, v141
	v_add_f32_e32 v9, v9, v10
	v_add_f32_e32 v10, v9, v8
	v_cvt_pk_bf16_f32 v8, v138, v139
	v_cvt_pk_bf16_f32 v9, v140, v141
	v_add_f32_e32 v11, v142, v143
	v_add_f32_e32 v134, v144, v145
	v_mfma_f32_32x32x16_bf16 v[98:113], v[162:165], v[150:153], v[98:113]
	v_add_f32_e32 v11, v11, v134
	v_add_f32_e32 v178, v11, v10
	v_cvt_pk_bf16_f32 v10, v142, v143
	v_cvt_pk_bf16_f32 v11, v144, v145
	ds_read_b128 v[138:141], v240 offset:40960
	ds_read_b128 v[134:137], v240 offset:45056
	s_add_i32 m0, s69, 0x2000
	s_cmp_le_i32 s89, s100
	global_load_lds_dwordx4 v243, s[90:91]
	s_waitcnt lgkmcnt(2)
	v_mfma_f32_32x32x16_bf16 v[82:97], v[14:17], v[154:157], v[82:97]
	v_add_f32_e32 v12, v114, v115
	v_add_f32_e32 v13, v116, v117
	v_add_f32_e32 v12, v12, v13
	v_add_f32_e32 v142, v12, v178
	v_cvt_pk_bf16_f32 v12, v114, v115
	v_cvt_pk_bf16_f32 v13, v116, v117
	v_mfma_f32_32x32x16_bf16 v[98:113], v[130:133], v[154:157], v[98:113]
	v_add_f32_e32 v14, v118, v119
	v_add_f32_e32 v15, v120, v121
	v_add_f32_e32 v14, v14, v15
	v_add_f32_e32 v16, v14, v142
	v_cvt_pk_bf16_f32 v14, v118, v119
	v_cvt_pk_bf16_f32 v15, v120, v121
	s_waitcnt lgkmcnt(0)
	v_mfma_f32_32x32x16_bf16 v[82:97], v[138:141], v[158:161], v[82:97]
	v_add_f32_e32 v17, v122, v123
	v_add_f32_e32 v130, v124, v125
	v_add_f32_e32 v17, v17, v130
	v_add_f32_e32 v16, v17, v16
	v_cvt_pk_bf16_f32 v178, v122, v123
	v_cvt_pk_bf16_f32 v179, v124, v125
	v_add_f32_e32 v17, v126, v127
	v_add_f32_e32 v130, v128, v129
	v_add_f32_e32 v17, v17, v130
	v_add_f32_e32 v16, v17, v16
	v_cvt_pk_bf16_f32 v180, v126, v127
	v_cvt_pk_bf16_f32 v181, v128, v129
	v_mfma_f32_32x32x16_bf16 v[98:113], v[134:137], v[158:161], v[98:113]
	ds_read_b64_tr_b16 v[194:195], v214 offset:0
	ds_read_b64_tr_b16 v[196:197], v214 offset:256
	ds_read_b64_tr_b16 v[190:191], v214 offset:4096
	ds_read_b64_tr_b16 v[192:193], v214 offset:4352
	ds_read_b64_tr_b16 v[186:187], v214 offset:8192
	ds_read_b64_tr_b16 v[188:189], v214 offset:8448
	ds_read_b64_tr_b16 v[182:183], v214 offset:12288
	ds_read_b64_tr_b16 v[184:185], v214 offset:12544
	s_cbranch_scc0 .Lp2s_disp2_u1
.LBB0_385_u1:
	s_waitcnt lgkmcnt(4)
	v_mfma_f32_32x32x16_bf16 v[66:81], v[4:7], v[194:197], v[66:81]
	v_exp_f32_e32 v82, v82
	v_exp_f32_e32 v98, v98
	ds_read_b64_tr_b16 v[114:115], v214 offset:512
	ds_read_b64_tr_b16 v[116:117], v214 offset:768
	v_mfma_f32_32x32x16_bf16 v[66:81], v[8:11], v[190:193], v[66:81]
	v_exp_f32_e32 v83, v83
	v_exp_f32_e32 v99, v99
	ds_read_b64_tr_b16 v[118:119], v214 offset:4608
	ds_read_b64_tr_b16 v[120:121], v214 offset:4864
	s_waitcnt lgkmcnt(4)
	v_mfma_f32_32x32x16_bf16 v[66:81], v[12:15], v[186:189], v[66:81]
	v_exp_f32_e32 v84, v84
	v_exp_f32_e32 v100, v100
	ds_read_b64_tr_b16 v[122:123], v214 offset:8704
	ds_read_b64_tr_b16 v[124:125], v214 offset:8960
	v_mfma_f32_32x32x16_bf16 v[66:81], v[178:181], v[182:185], v[66:81]
	v_exp_f32_e32 v85, v85
	v_exp_f32_e32 v101, v101
	ds_read_b64_tr_b16 v[126:127], v214 offset:12800
	ds_read_b64_tr_b16 v[128:129], v214 offset:13056
	s_waitcnt lgkmcnt(4)
	v_mfma_f32_32x32x16_bf16 v[50:65], v[4:7], v[114:117], v[50:65]
	v_exp_f32_e32 v86, v86
	v_exp_f32_e32 v102, v102
	v_exp_f32_e32 v94, v94
	ds_read_b64_tr_b16 v[130:131], v214 offset:1024
	ds_read_b64_tr_b16 v[132:133], v214 offset:1280
	v_mfma_f32_32x32x16_bf16 v[50:65], v[8:11], v[118:121], v[50:65]
	v_exp_f32_e32 v87, v87
	v_exp_f32_e32 v103, v103
	v_exp_f32_e32 v110, v110
	ds_read_b64_tr_b16 v[134:135], v214 offset:5120
	ds_read_b64_tr_b16 v[136:137], v214 offset:5376
	s_waitcnt lgkmcnt(4)
	v_mfma_f32_32x32x16_bf16 v[50:65], v[12:15], v[122:125], v[50:65]
	v_exp_f32_e32 v88, v88
	v_exp_f32_e32 v104, v104
	v_exp_f32_e32 v95, v95
	ds_read_b64_tr_b16 v[138:139], v214 offset:9216
	ds_read_b64_tr_b16 v[140:141], v214 offset:9472
	v_mfma_f32_32x32x16_bf16 v[50:65], v[178:181], v[126:129], v[50:65]
	v_exp_f32_e32 v89, v89
	v_exp_f32_e32 v105, v105
	v_exp_f32_e32 v111, v111
	ds_read_b64_tr_b16 v[142:143], v214 offset:13312
	ds_read_b64_tr_b16 v[144:145], v214 offset:13568
	s_waitcnt lgkmcnt(4)
	v_mfma_f32_32x32x16_bf16 v[34:49], v[4:7], v[130:133], v[34:49]
	v_exp_f32_e32 v90, v90
	v_exp_f32_e32 v106, v106
	v_exp_f32_e32 v96, v96
	ds_read_b64_tr_b16 v[114:115], v214 offset:1536
	ds_read_b64_tr_b16 v[116:117], v214 offset:1792
	v_mfma_f32_32x32x16_bf16 v[34:49], v[8:11], v[134:137], v[34:49]
	v_exp_f32_e32 v91, v91
	v_exp_f32_e32 v107, v107
	v_exp_f32_e32 v112, v112
	ds_read_b64_tr_b16 v[118:119], v214 offset:5632
	ds_read_b64_tr_b16 v[120:121], v214 offset:5888
	s_waitcnt lgkmcnt(4)
	v_mfma_f32_32x32x16_bf16 v[34:49], v[12:15], v[138:141], v[34:49]
	v_exp_f32_e32 v92, v92
	v_exp_f32_e32 v108, v108
	v_exp_f32_e32 v97, v97
	ds_read_b64_tr_b16 v[122:123], v214 offset:9728
	ds_read_b64_tr_b16 v[124:125], v214 offset:9984
	v_mfma_f32_32x32x16_bf16 v[34:49], v[178:181], v[142:145], v[34:49]
	v_exp_f32_e32 v93, v93
	v_exp_f32_e32 v109, v109
	v_exp_f32_e32 v113, v113
	ds_read_b64_tr_b16 v[126:127], v214 offset:13824
	ds_read_b64_tr_b16 v[128:129], v214 offset:14080
	s_waitcnt vmcnt(3) lgkmcnt(0)
	s_barrier
	s_cmp_gt_i32 s62, s60
	s_cbranch_scc1 .LBB0_394_u1
	ds_read_b128 v[174:177], v237 offset:49152
	ds_read_b128 v[170:173], v237 offset:53248
	ds_read_b128 v[166:169], v238 offset:49152
	ds_read_b128 v[162:165], v238 offset:53248

; #define SBAR() __builtin_amdgcn_sched_barrier(0)
; #define VRD(i) do { if constexpr (VAR & 2) break; lo[(i) & 3] = vtr(vb + v_rd_off((i) >> 2, (i) & 3, 0)); hv[(i) & 3] = vtr(vb + v_rd_off((i) >> 2, (i) & 3, 1)); } while (0)
; template <int VAR> ...
;     ...
;     float ps = 0.f;
;     if constexpr (VAR & 4) { ka[0] = qr[0]; ka[1] = qr[1]; ka[2] = qr[2]; ka[3] = qr[3]; kb[0] = qr[0]; kb[1] = qr[1]; kb[2] = qr[2]; kb[3] = qr[3]; }
;     ka[0] = kp[0]; kb[0] = kp[1]; ka[1] = kp[2]; kb[1] = kp[3]; if (dk) glds16(gk, lk); SBAR();
;     { const f32x16 z = f32x16{};
;       QKM(x0, ka[0], qr[0], z);  SUM4(y0, 0); PKA(y0, 0);       SBAR();
;       QKM(x1, kb[0], qr[0], z);  SUM4(y0, 4); PKB(y0, 4, pa0);  KRD(2); if (dv) glds16(gv, lv); SBAR(); }
;     QKM(x0, ka[1], qr[1], x0); SUM4(y0, 8); PKA(y0, 8);       SBAR();
;     QKM(x1, kb[1], qr[1], x1); SUM4(y0, 12); PKB(y0, 12, pa1); KRD(3); if (dv) glds16(gv + 8192, lv + 8192); SBAR();
;     QKM(x0, ka[2], qr[2], x0); SUM4(y1, 0); PKA(y1, 0);       SBAR();
;     QKM(x1, kb[2], qr[2], x1); SUM4(y1, 4); PKB(y1, 4, pa2);  SBAR();
;     QKM(x0, ka[3], qr[3], x0); SUM4(y1, 8); PKA(y1, 8);       SBAR();
;     QKM(x1, kb[3], qr[3], x1); SUM4(y1, 12); PKB(y1, 12, pa3); VRD(0); VRD(1); SBAR();
;     VRD(2); VRD(3); SBAR();
;     if (near) {
;         float tA[4], uA[4], tB[4], uB[4];
;     ...
;         TLD(tA, uA, 0); SBAR(); TLD(tB, uB, 1); SBAR();
;         asm volatile("s_nop 15\n\ts_nop 7" : "+v"(x0), "+v"(x1));
;         TAD(tA, uA, 0); SBAR(); TLD(tA, uA, 2); SBAR(); TAD(tB, uB, 1); SBAR(); TLD(tB, uB, 3); SBAR(); TAD(tA, uA, 2); SBAR(); TAD(tB, uB, 3);
;     ...
;     } else if (__builtin_expect(shift != 0.f, 0)) {
;         asm volatile("s_nop 15\n\ts_nop 7" : "+v"(x0), "+v"(x1));
; #pragma unroll
;         for (int r = 0; r < 16; ++r) { asm volatile("v_sub_f32 %0, %0, %1" : "+v"(x0[r]) : "v"(shift)); asm volatile("v_sub_f32 %0, %0, %1" : "+v"(x1[r]) : "v"(shift)); }
;     }
;     SBAR();
;     ...
;     GAPB(0, pa0); GAPB(1, pa1); GAPB(2, pa2); GAPB(3, pa3); GAPB(4, pa0); GAPB(5, pa1); GAPB(6, pa2); GAPB(7, pa3);
;     GAPB(8, pa0); GAPB(9, pa1); GAPB(10, pa2); GAPB(11, pa3);
;     if (wv == 3) asm volatile("s_waitcnt vmcnt(3)" ::: "memory"); else if (wv == 2) asm volatile("s_waitcnt vmcnt(2)" ::: "memory"); else asm volatile("s_waitcnt vmcnt(0)" ::: "memory");
;     asm volatile("s_waitcnt lgkmcnt(0)\n\ts_barrier" ::: "memory");
.Lp2u_top2:
	s_add_i32 s62, s20, 1
	s_add_i32 m0, s88, 0x2000
	s_mov_b32 s66, s87
	global_load_lds_dwordx4 v198, s[0:1]
	s_waitcnt lgkmcnt(2)
	v_mfma_f32_32x32x16_bf16 v[130:145], v[174:177], v[146:149], 0
	v_add_f32_e32 v4, v82, v83
	v_add_f32_e32 v5, v84, v85
	v_add_f32_e32 v6, v4, v5
	v_cvt_pk_bf16_f32 v4, v82, v83
	v_cvt_pk_bf16_f32 v5, v84, v85
	v_add_f32_e32 v7, v86, v87
	v_add_f32_e32 v8, v88, v89
	v_mfma_f32_32x32x16_bf16 v[114:129], v[170:173], v[146:149], 0
	v_add_f32_e32 v7, v7, v8
	v_add_f32_e32 v8, v7, v6
	v_cvt_pk_bf16_f32 v6, v86, v87
	v_cvt_pk_bf16_f32 v7, v88, v89
	s_mov_b32 m0, s66
	ds_read_b128 v[14:17], v239 offset:49152
	ds_read_b128 v[86:89], v239 offset:53248
	global_load_lds_dwordx4 v198, s[90:91]
	s_waitcnt lgkmcnt(2)
	v_mfma_f32_32x32x16_bf16 v[130:145], v[166:169], v[150:153], v[130:145]
	v_add_f32_e32 v9, v90, v91
	v_add_f32_e32 v10, v92, v93
	v_add_f32_e32 v9, v9, v10
	v_add_f32_e32 v10, v9, v8
	v_cvt_pk_bf16_f32 v8, v90, v91
	v_cvt_pk_bf16_f32 v9, v92, v93
	v_add_f32_e32 v11, v94, v95
	v_add_f32_e32 v13, v96, v97
	v_mfma_f32_32x32x16_bf16 v[114:129], v[162:165], v[150:153], v[114:129]
	v_add_f32_e32 v11, v11, v13
	v_add_f32_e32 v13, v11, v10
	v_cvt_pk_bf16_f32 v10, v94, v95
	v_cvt_pk_bf16_f32 v11, v96, v97
	ds_read_b128 v[90:93], v240 offset:49152
	ds_read_b128 v[82:85], v240 offset:53248
	s_add_i32 m0, s66, 0x2000
	s_cmp_le_i32 s89, s101
	global_load_lds_dwordx4 v241, s[90:91]
	s_waitcnt lgkmcnt(2)
	v_mfma_f32_32x32x16_bf16 v[130:145], v[14:17], v[154:157], v[130:145]
	v_add_f32_e32 v12, v98, v99
	v_add_f32_e32 v94, v100, v101
	v_add_f32_e32 v12, v12, v94
	v_add_f32_e32 v94, v12, v13
	v_cvt_pk_bf16_f32 v12, v98, v99
	v_cvt_pk_bf16_f32 v13, v100, v101
	v_mfma_f32_32x32x16_bf16 v[114:129], v[86:89], v[154:157], v[114:129]
	v_add_f32_e32 v14, v102, v103
	v_add_f32_e32 v15, v104, v105
	v_add_f32_e32 v14, v14, v15
	v_add_f32_e32 v16, v14, v94
	v_cvt_pk_bf16_f32 v14, v102, v103
	v_cvt_pk_bf16_f32 v15, v104, v105
	s_waitcnt lgkmcnt(0)
	v_mfma_f32_32x32x16_bf16 v[130:145], v[90:93], v[158:161], v[130:145]
	v_add_f32_e32 v17, v106, v107
	v_add_f32_e32 v86, v108, v109
	v_add_f32_e32 v17, v17, v86
	v_add_f32_e32 v16, v17, v16
	v_cvt_pk_bf16_f32 v178, v106, v107
	v_cvt_pk_bf16_f32 v179, v108, v109
	v_add_f32_e32 v17, v110, v111
	v_add_f32_e32 v86, v112, v113
	v_add_f32_e32 v17, v17, v86
	v_add_f32_e32 v229, v17, v16
	v_cvt_pk_bf16_f32 v180, v110, v111
	v_cvt_pk_bf16_f32 v181, v112, v113
	v_mfma_f32_32x32x16_bf16 v[114:129], v[82:85], v[158:161], v[114:129]
	ds_read_b64_tr_b16 v[174:175], v214 offset:16384
	ds_read_b64_tr_b16 v[176:177], v214 offset:16640
	ds_read_b64_tr_b16 v[170:171], v214 offset:20480
	ds_read_b64_tr_b16 v[172:173], v214 offset:20736
	ds_read_b64_tr_b16 v[166:167], v214 offset:24576
	ds_read_b64_tr_b16 v[168:169], v214 offset:24832
	ds_read_b64_tr_b16 v[162:163], v214 offset:28672
	ds_read_b64_tr_b16 v[164:165], v214 offset:28928
	s_cbranch_scc0 .Lp2s_disp1_u2
.LBB0_367_u2:
	s_waitcnt lgkmcnt(4)
	v_mfma_f32_32x32x16_bf16 v[66:81], v[4:7], v[174:177], v[66:81]
	v_exp_f32_e32 v130, v130
	v_exp_f32_e32 v114, v114
	ds_read_b64_tr_b16 v[98:99], v214 offset:16896
	ds_read_b64_tr_b16 v[100:101], v214 offset:17152
	v_mfma_f32_32x32x16_bf16 v[66:81], v[8:11], v[170:173], v[66:81]
	v_exp_f32_e32 v131, v131
	v_exp_f32_e32 v115, v115
	ds_read_b64_tr_b16 v[102:103], v214 offset:20992
	ds_read_b64_tr_b16 v[104:105], v214 offset:21248
	s_waitcnt lgkmcnt(4)
	v_mfma_f32_32x32x16_bf16 v[66:81], v[12:15], v[166:169], v[66:81]
	v_exp_f32_e32 v132, v132
	v_exp_f32_e32 v116, v116
	ds_read_b64_tr_b16 v[106:107], v214 offset:25088
	ds_read_b64_tr_b16 v[108:109], v214 offset:25344
	v_mfma_f32_32x32x16_bf16 v[66:81], v[178:181], v[162:165], v[66:81]
	v_exp_f32_e32 v133, v133
	v_exp_f32_e32 v117, v117
	ds_read_b64_tr_b16 v[110:111], v214 offset:29184
	ds_read_b64_tr_b16 v[112:113], v214 offset:29440
	s_waitcnt lgkmcnt(4)
	v_mfma_f32_32x32x16_bf16 v[50:65], v[4:7], v[98:101], v[50:65]
	v_exp_f32_e32 v134, v134
	v_exp_f32_e32 v118, v118
	v_exp_f32_e32 v142, v142
	ds_read_b64_tr_b16 v[82:83], v214 offset:17408
	ds_read_b64_tr_b16 v[84:85], v214 offset:17664
	v_mfma_f32_32x32x16_bf16 v[50:65], v[8:11], v[102:105], v[50:65]
	v_exp_f32_e32 v135, v135
	v_exp_f32_e32 v119, v119
	v_exp_f32_e32 v126, v126
	ds_read_b64_tr_b16 v[86:87], v214 offset:21504
	ds_read_b64_tr_b16 v[88:89], v214 offset:21760
	s_waitcnt lgkmcnt(4)
	v_mfma_f32_32x32x16_bf16 v[50:65], v[12:15], v[106:109], v[50:65]
	v_exp_f32_e32 v136, v136
	v_exp_f32_e32 v120, v120
	v_exp_f32_e32 v143, v143
	ds_read_b64_tr_b16 v[90:91], v214 offset:25600
	ds_read_b64_tr_b16 v[92:93], v214 offset:25856
	v_mfma_f32_32x32x16_bf16 v[50:65], v[178:181], v[110:113], v[50:65]
	v_exp_f32_e32 v137, v137
	v_exp_f32_e32 v121, v121
	v_exp_f32_e32 v127, v127
	ds_read_b64_tr_b16 v[94:95], v214 offset:29696
	ds_read_b64_tr_b16 v[96:97], v214 offset:29952
	s_waitcnt lgkmcnt(4)
	v_mfma_f32_32x32x16_bf16 v[34:49], v[4:7], v[82:85], v[34:49]
	v_exp_f32_e32 v138, v138
	v_exp_f32_e32 v122, v122
	v_exp_f32_e32 v144, v144
	ds_read_b64_tr_b16 v[98:99], v214 offset:17920
	ds_read_b64_tr_b16 v[100:101], v214 offset:18176
	v_mfma_f32_32x32x16_bf16 v[34:49], v[8:11], v[86:89], v[34:49]
	v_exp_f32_e32 v139, v139
	v_exp_f32_e32 v123, v123
	v_exp_f32_e32 v128, v128
	ds_read_b64_tr_b16 v[102:103], v214 offset:22016
	ds_read_b64_tr_b16 v[104:105], v214 offset:22272
	s_waitcnt lgkmcnt(4)
	v_mfma_f32_32x32x16_bf16 v[34:49], v[12:15], v[90:93], v[34:49]
	v_exp_f32_e32 v140, v140
	v_exp_f32_e32 v124, v124
	v_exp_f32_e32 v145, v145
	ds_read_b64_tr_b16 v[106:107], v214 offset:26112
	ds_read_b64_tr_b16 v[108:109], v214 offset:26368
	v_mfma_f32_32x32x16_bf16 v[34:49], v[178:181], v[94:97], v[34:49]
	v_exp_f32_e32 v141, v141
	v_exp_f32_e32 v125, v125
	v_exp_f32_e32 v129, v129
	ds_read_b64_tr_b16 v[110:111], v214 offset:30208
	ds_read_b64_tr_b16 v[112:113], v214 offset:30464
	s_waitcnt vmcnt(3) lgkmcnt(0)
	s_barrier
; #define SBAR() __builtin_amdgcn_sched_barrier(0)
; #define KRD(d0) do { if constexpr (VAR & 4) break; const char* a_ = Kc + (((2 * (d0) + hi) ^ sw) << 4); ka[d0] = *reinterpret_cast<const bf16x8*>(a_); kb[d0] = *reinterpret_cast<const bf16x8*>(a_ + 32 * 128); } while (0)
; #define VRD(i) do { if constexpr (VAR & 2) break; lo[(i) & 3] = vtr(vb + v_rd_off((i) >> 2, (i) & 3, 0)); hv[(i) & 3] = vtr(vb + v_rd_off((i) >> 2, (i) & 3, 1)); } while (0)
; #define SUM4(Y, b) do { if constexpr (!(VAR & 8)) { ps += (Y[b] + Y[(b) + 1]) + (Y[(b) + 2] + Y[(b) + 3]); asm volatile("" : "+v"(ps)); } } while (0)
; #define PKA(Y, b) do { if constexpr (!(VAR & 8)) { a0 = cvtpk(Y[b], Y[(b) + 1]); a1 = cvtpk(Y[(b) + 2], Y[(b) + 3]); } } while (0)
; #define QKM(X, KF, QF, C) do { if constexpr (VAR & 4) { X = C; asm volatile("" : "+v"(X)); } else X = __builtin_amdgcn_mfma_f32_32x32x16_bf16(KF, QF, C, 0, 0, 0); } while (0)
; template <int VAR> ...
;     ...
;     float ps = 0.f;
;     if constexpr (VAR & 4) { ka[0] = qr[0]; ka[1] = qr[1]; ka[2] = qr[2]; ka[3] = qr[3]; kb[0] = qr[0]; kb[1] = qr[1]; kb[2] = qr[2]; kb[3] = qr[3]; }
;     ka[0] = kp[0]; kb[0] = kp[1]; ka[1] = kp[2]; kb[1] = kp[3]; if (dk) glds16(gk, lk); SBAR();
;     { const f32x16 z = f32x16{};
;       QKM(x0, ka[0], qr[0], z);  SUM4(y0, 0); PKA(y0, 0);       SBAR();
;       QKM(x1, kb[0], qr[0], z);  SUM4(y0, 4); PKB(y0, 4, pa0);  KRD(2); if (dv) glds16(gv, lv); SBAR(); }
;     QKM(x0, ka[1], qr[1], x0); SUM4(y0, 8); PKA(y0, 8);       SBAR();
;     QKM(x1, kb[1], qr[1], x1); SUM4(y0, 12); PKB(y0, 12, pa1); KRD(3); if (dv) glds16(gv + 8192, lv + 8192); SBAR();
;     QKM(x0, ka[2], qr[2], x0); SUM4(y1, 0); PKA(y1, 0);       SBAR();
;     QKM(x1, kb[2], qr[2], x1); SUM4(y1, 4); PKB(y1, 4, pa2);  SBAR();
;     QKM(x0, ka[3], qr[3], x0); SUM4(y1, 8); PKA(y1, 8);       SBAR();
;     QKM(x1, kb[3], qr[3], x1); SUM4(y1, 12); PKB(y1, 12, pa3); VRD(0); VRD(1); SBAR();
;     VRD(2); VRD(3); SBAR();
;     ...
;     if (pre) { const char* a0_ = Kn + (((0 + hi) ^ sw) << 4); const char* a1_ = Kn + (((2 + hi) ^ sw) << 4);
;         kp[0] = *reinterpret_cast<const bf16x8*>(a0_); kp[1] = *reinterpret_cast<const bf16x8*>(a0_ + 32 * 128); kp[2] = *reinterpret_cast<const bf16x8*>(a1_); kp[3] = *reinterpret_cast<const bf16x8*>(a1_ + 32 * 128); }
;     SBAR();
;     GAPB(12, pa0); GAPB(13, pa1); GAPB(14, pa2); GAPB(15, pa3);
;     l_reg += ps;
	ds_read_b128 v[174:177], v237 offset:32768
	ds_read_b128 v[170:173], v237 offset:36864
	ds_read_b128 v[166:169], v238 offset:32768
	ds_read_b128 v[162:165], v238 offset:36864
	v_mfma_f32_32x32x16_bf16 v[18:33], v[4:7], v[98:101], v[18:33]
	v_mfma_f32_32x32x16_bf16 v[18:33], v[8:11], v[102:105], v[18:33]
	v_mfma_f32_32x32x16_bf16 v[18:33], v[12:15], v[106:109], v[18:33]
	v_mfma_f32_32x32x16_bf16 v[18:33], v[178:181], v[110:113], v[18:33]
	s_add_i32 s20, s20, 2
	s_add_i32 m0, s88, 0x4000
	s_add_i32 s69, s87, 0x4000
	global_load_lds_dwordx4 v241, s[0:1]
	s_waitcnt lgkmcnt(2)
	v_mfma_f32_32x32x16_bf16 v[82:97], v[174:177], v[146:149], 0
	v_add_f32_e32 v4, v130, v131
	v_add_f32_e32 v5, v132, v133
	v_add_f32_e32 v6, v4, v5
	v_cvt_pk_bf16_f32 v4, v130, v131
	v_cvt_pk_bf16_f32 v5, v132, v133
	v_add_f32_e32 v7, v134, v135
	v_add_f32_e32 v8, v136, v137
	v_mfma_f32_32x32x16_bf16 v[98:113], v[170:173], v[146:149], 0
	v_add_f32_e32 v7, v7, v8
	v_add_f32_e32 v8, v7, v6
	v_cvt_pk_bf16_f32 v6, v134, v135
	v_cvt_pk_bf16_f32 v7, v136, v137
	s_mov_b32 m0, s69
	ds_read_b128 v[14:17], v239 offset:32768
	ds_read_b128 v[130:133], v239 offset:36864
	global_load_lds_dwordx4 v242, s[90:91]
	s_waitcnt lgkmcnt(2)
	v_mfma_f32_32x32x16_bf16 v[82:97], v[166:169], v[150:153], v[82:97]
	v_add_f32_e32 v9, v138, v139
	v_add_f32_e32 v10, v140, v141
	v_add_f32_e32 v9, v9, v10
	v_add_f32_e32 v10, v9, v8
	v_cvt_pk_bf16_f32 v8, v138, v139
	v_cvt_pk_bf16_f32 v9, v140, v141
	v_add_f32_e32 v11, v142, v143
	v_add_f32_e32 v134, v144, v145
	v_mfma_f32_32x32x16_bf16 v[98:113], v[162:165], v[150:153], v[98:113]
	v_add_f32_e32 v11, v11, v134
	v_add_f32_e32 v178, v11, v10
	v_cvt_pk_bf16_f32 v10, v142, v143
	v_cvt_pk_bf16_f32 v11, v144, v145
	ds_read_b128 v[138:141], v240 offset:32768
	ds_read_b128 v[134:137], v240 offset:36864
	s_add_i32 m0, s69, 0x2000
	s_cmp_le_i32 s89, s100
	global_load_lds_dwordx4 v243, s[90:91]
	s_waitcnt lgkmcnt(2)
	v_mfma_f32_32x32x16_bf16 v[82:97], v[14:17], v[154:157], v[82:97]
	v_add_f32_e32 v12, v114, v115
	v_add_f32_e32 v13, v116, v117
	v_add_f32_e32 v12, v12, v13
	v_add_f32_e32 v142, v12, v178
	v_cvt_pk_bf16_f32 v12, v114, v115
	v_cvt_pk_bf16_f32 v13, v116, v117
	v_mfma_f32_32x32x16_bf16 v[98:113], v[130:133], v[154:157], v[98:113]
	v_add_f32_e32 v14, v118, v119
	v_add_f32_e32 v15, v120, v121
	v_add_f32_e32 v14, v14, v15
	v_add_f32_e32 v16, v14, v142
	v_cvt_pk_bf16_f32 v14, v118, v119
	v_cvt_pk_bf16_f32 v15, v120, v121
	s_waitcnt lgkmcnt(0)
	v_mfma_f32_32x32x16_bf16 v[82:97], v[138:141], v[158:161], v[82:97]
	v_add_f32_e32 v17, v122, v123
	v_add_f32_e32 v130, v124, v125
	v_add_f32_e32 v17, v17, v130
	v_add_f32_e32 v16, v17, v16
	v_cvt_pk_bf16_f32 v178, v122, v123
	v_cvt_pk_bf16_f32 v179, v124, v125
	v_add_f32_e32 v17, v126, v127
	v_add_f32_e32 v130, v128, v129
	v_add_f32_e32 v17, v17, v130
	v_add_f32_e32 v16, v17, v16
	v_cvt_pk_bf16_f32 v180, v126, v127
	v_cvt_pk_bf16_f32 v181, v128, v129
	v_mfma_f32_32x32x16_bf16 v[98:113], v[134:137], v[158:161], v[98:113]
	ds_read_b64_tr_b16 v[194:195], v214 offset:32768
	ds_read_b64_tr_b16 v[196:197], v214 offset:33024
	ds_read_b64_tr_b16 v[190:191], v214 offset:36864
	ds_read_b64_tr_b16 v[192:193], v214 offset:37120
	ds_read_b64_tr_b16 v[186:187], v214 offset:40960
	ds_read_b64_tr_b16 v[188:189], v214 offset:41216
	ds_read_b64_tr_b16 v[182:183], v214 offset:45056
	ds_read_b64_tr_b16 v[184:185], v214 offset:45312
	s_cbranch_scc0 .Lp2s_disp2_u2
; #define SBAR() __builtin_amdgcn_sched_barrier(0)
; template <int VAR> ...
;     ...
;     GAPB(0, pa0); GAPB(1, pa1); GAPB(2, pa2); GAPB(3, pa3); GAPB(4, pa0); GAPB(5, pa1); GAPB(6, pa2); GAPB(7, pa3);
;     GAPB(8, pa0); GAPB(9, pa1); GAPB(10, pa2); GAPB(11, pa3);
;     if (wv == 3) asm volatile("s_waitcnt vmcnt(3)" ::: "memory"); else if (wv == 2) asm volatile("s_waitcnt vmcnt(2)" ::: "memory"); else asm volatile("s_waitcnt vmcnt(0)" ::: "memory");
;     asm volatile("s_waitcnt lgkmcnt(0)\n\ts_barrier" ::: "memory");
;     if (pre) { const char* a0_ = Kn + (((0 + hi) ^ sw) << 4); const char* a1_ = Kn + (((2 + hi) ^ sw) << 4);
;         kp[0] = *reinterpret_cast<const bf16x8*>(a0_); kp[1] = *reinterpret_cast<const bf16x8*>(a0_ + 32 * 128); kp[2] = *reinterpret_cast<const bf16x8*>(a1_); kp[3] = *reinterpret_cast<const bf16x8*>(a1_ + 32 * 128); }
;     SBAR();
;     GAPB(12, pa0); GAPB(13, pa1); GAPB(14, pa2); GAPB(15, pa3);
;     l_reg += ps;
; template <int VAR>
; __device__ __forceinline__ void dattn_block(const BlockRef& cur, const BlockRef& nxt, bool has_next, char* lds, Seam& S, const Outs& OU) {
;     ...
;     const int TL1 = __builtin_amdgcn_readfirstlane((qlo + 31) / KVBLK + 1);
;     int t = 1;
;     for (; t + 1 < TL1; t += 2) { STEP(pB0, pB1, pA0, pA1, t); STEP(pA0, pA1, pB0, pB1, t + 1); }
.LBB0_385_u2:
	s_waitcnt lgkmcnt(4)
	v_mfma_f32_32x32x16_bf16 v[66:81], v[4:7], v[194:197], v[66:81]
	v_exp_f32_e32 v82, v82
	v_exp_f32_e32 v98, v98
	ds_read_b64_tr_b16 v[114:115], v214 offset:33280
	ds_read_b64_tr_b16 v[116:117], v214 offset:33536
	v_mfma_f32_32x32x16_bf16 v[66:81], v[8:11], v[190:193], v[66:81]
	v_exp_f32_e32 v83, v83
	v_exp_f32_e32 v99, v99
	ds_read_b64_tr_b16 v[118:119], v214 offset:37376
	ds_read_b64_tr_b16 v[120:121], v214 offset:37632
	s_waitcnt lgkmcnt(4)
	v_mfma_f32_32x32x16_bf16 v[66:81], v[12:15], v[186:189], v[66:81]
	v_exp_f32_e32 v84, v84
	v_exp_f32_e32 v100, v100
	ds_read_b64_tr_b16 v[122:123], v214 offset:41472
	ds_read_b64_tr_b16 v[124:125], v214 offset:41728
	v_mfma_f32_32x32x16_bf16 v[66:81], v[178:181], v[182:185], v[66:81]
	v_exp_f32_e32 v85, v85
	v_exp_f32_e32 v101, v101
	ds_read_b64_tr_b16 v[126:127], v214 offset:45568
	ds_read_b64_tr_b16 v[128:129], v214 offset:45824
	s_waitcnt lgkmcnt(4)
	v_mfma_f32_32x32x16_bf16 v[50:65], v[4:7], v[114:117], v[50:65]
	v_exp_f32_e32 v86, v86
	v_exp_f32_e32 v102, v102
	v_exp_f32_e32 v94, v94
	ds_read_b64_tr_b16 v[130:131], v214 offset:33792
	ds_read_b64_tr_b16 v[132:133], v214 offset:34048
	v_mfma_f32_32x32x16_bf16 v[50:65], v[8:11], v[118:121], v[50:65]
	v_exp_f32_e32 v87, v87
	v_exp_f32_e32 v103, v103
	v_exp_f32_e32 v110, v110
	ds_read_b64_tr_b16 v[134:135], v214 offset:37888
	ds_read_b64_tr_b16 v[136:137], v214 offset:38144
	s_waitcnt lgkmcnt(4)
	v_mfma_f32_32x32x16_bf16 v[50:65], v[12:15], v[122:125], v[50:65]
	v_exp_f32_e32 v88, v88
	v_exp_f32_e32 v104, v104
	v_exp_f32_e32 v95, v95
	ds_read_b64_tr_b16 v[138:139], v214 offset:41984
	ds_read_b64_tr_b16 v[140:141], v214 offset:42240
	v_mfma_f32_32x32x16_bf16 v[50:65], v[178:181], v[126:129], v[50:65]
	v_exp_f32_e32 v89, v89
	v_exp_f32_e32 v105, v105
	v_exp_f32_e32 v111, v111
	ds_read_b64_tr_b16 v[142:143], v214 offset:46080
	ds_read_b64_tr_b16 v[144:145], v214 offset:46336
	s_waitcnt lgkmcnt(4)
	v_mfma_f32_32x32x16_bf16 v[34:49], v[4:7], v[130:133], v[34:49]
	v_exp_f32_e32 v90, v90
	v_exp_f32_e32 v106, v106
	v_exp_f32_e32 v96, v96
	ds_read_b64_tr_b16 v[114:115], v214 offset:34304
	ds_read_b64_tr_b16 v[116:117], v214 offset:34560
	v_mfma_f32_32x32x16_bf16 v[34:49], v[8:11], v[134:137], v[34:49]
	v_exp_f32_e32 v91, v91
	v_exp_f32_e32 v107, v107
	v_exp_f32_e32 v112, v112
	ds_read_b64_tr_b16 v[118:119], v214 offset:38400
	ds_read_b64_tr_b16 v[120:121], v214 offset:38656
	s_waitcnt lgkmcnt(4)
	v_mfma_f32_32x32x16_bf16 v[34:49], v[12:15], v[138:141], v[34:49]
	v_exp_f32_e32 v92, v92
	v_exp_f32_e32 v108, v108
	v_exp_f32_e32 v97, v97
	ds_read_b64_tr_b16 v[122:123], v214 offset:42496
	ds_read_b64_tr_b16 v[124:125], v214 offset:42752
	v_mfma_f32_32x32x16_bf16 v[34:49], v[178:181], v[142:145], v[34:49]
	v_exp_f32_e32 v93, v93
	v_exp_f32_e32 v109, v109
	v_exp_f32_e32 v113, v113
	ds_read_b64_tr_b16 v[126:127], v214 offset:46592
	ds_read_b64_tr_b16 v[128:129], v214 offset:46848
	s_waitcnt vmcnt(3) lgkmcnt(0)
	s_barrier
	s_cmp_gt_i32 s62, s60
	s_cbranch_scc1 .LBB0_394_u2
	ds_read_b128 v[174:177], v237 offset:40960
	ds_read_b128 v[170:173], v237 offset:45056
	ds_read_b128 v[166:169], v238 offset:40960
	ds_read_b128 v[162:165], v238 offset:45056
.LBB0_394_u2:
	v_add_f32_e32 v17, v227, v229
	v_mfma_f32_32x32x16_bf16 v[18:33], v[4:7], v[114:117], v[18:33]
	v_mfma_f32_32x32x16_bf16 v[18:33], v[8:11], v[118:121], v[18:33]
	v_mfma_f32_32x32x16_bf16 v[18:33], v[12:15], v[122:125], v[18:33]
	v_mfma_f32_32x32x16_bf16 v[18:33], v[178:181], v[126:129], v[18:33]
	s_addk_i32 s89, 0x80
	v_add_f32_e32 v227, v17, v16
	v_add_u32_e32 v3, 0xfffffe00, v3
	s_add_u32 s90, s90, 0x8000
	s_addc_u32 s91, s91, 0
	s_add_u32 s0, s0, 0x4000
	s_addc_u32 s1, s1, 0
	s_cmp_lt_i32 s62, s60
	s_cbranch_scc0 .Lp2u_exit2
	s_branch .LBB0_356


; template <int VAR>
; __device__ __forceinline__ void dattn_block(const BlockRef& cur, const BlockRef& nxt, bool has_next, char* lds, Seam& S, const Outs& OU) {
;     ...
;     int s_prev = 0, s_cur = 0, s_next = 1;
;     ...
;     for (; t + 1 < TL1; t += 2) { STEP(pB0, pB1, pA0, pA1, t); STEP(pA0, pA1, pB0, pB1, t + 1); }
.Lp2u_exit0:
	s_movk_i32 s86, 0x4000
	s_movk_i32 s68, 0x0
	s_movk_i32 s66, 0x2000
	s_branch .LBB0_403

; template <int VAR>
; __device__ __forceinline__ void dattn_block(const BlockRef& cur, const BlockRef& nxt, bool has_next, char* lds, Seam& S, const Outs& OU) {
;     ...
;     int s_prev = 0, s_cur = 0, s_next = 1;
;     ...
;     for (; t + 1 < TL1; t += 2) { STEP(pB0, pB1, pA0, pA1, t); STEP(pA0, pA1, pB0, pB1, t + 1); }
.Lp2u_exit1:
	s_movk_i32 s86, 0x2000
	s_movk_i32 s68, 0x4000
	s_movk_i32 s66, 0x0
	s_branch .LBB0_403

; template <int VAR>
; __device__ __forceinline__ void dattn_block(const BlockRef& cur, const BlockRef& nxt, bool has_next, char* lds, Seam& S, const Outs& OU) {
;     ...
;     int s_prev = 0, s_cur = 0, s_next = 1;
;     ...
;     for (; t + 1 < TL1; t += 2) { STEP(pB0, pB1, pA0, pA1, t); STEP(pA0, pA1, pB0, pB1, t + 1); }
.Lp2u_exit2:
	s_movk_i32 s86, 0x0
	s_movk_i32 s68, 0x2000
	s_movk_i32 s66, 0x4000
	s_branch .LBB0_403
